# nt also on the final f32 output stores of the L1 down epilogue (never re-read)
# speedup vs baseline: 1.0016x; 1.0016x over previous
.LBB0_1718:
	s_or_b64 exec, exec, s[2:3]
	s_lshl_b32 s0, s24, 5
	s_and_b32 s0, s0, 0xfffffc00
	s_ashr_i32 s1, s0, 31
	s_lshl_b32 s2, s25, 5
	s_lshl_b64 s[0:1], s[0:1], 2
	s_add_u32 s0, s34, s0
	s_addc_u32 s1, s35, s1
	s_lshl_b32 s3, s8, 8
	v_lshrrev_b32_e32 v0, 2, v0
	s_or_b32 s2, s3, s2
	v_add_u32_e32 v146, s4, v149
	v_and_or_b32 v0, v0, 12, s2
	v_ashrrev_i32_e32 v147, 31, v146
	v_ashrrev_i32_e32 v1, 31, v0
	v_lshlrev_b64 v[134:135], 10, v[146:147]
	v_lshl_add_u64 v[134:135], v[134:135], 0, v[0:1]
	v_lshlrev_b64 v[154:155], 1, v[134:135]
	v_lshl_add_u64 v[130:131], v[0:1], 2, s[0:1]
	s_waitcnt lgkmcnt(0)
	s_barrier
	s_mov_b32 s0, 0x112000
	v_lshl_add_u64 v[136:137], s[56:57], 0, v[154:155]
	v_add_co_u32_e32 v136, vcc, s0, v130
	v_lshl_add_u32 v133, v149, 3, 0
	s_nop 0
	v_addc_co_u32_e32 v137, vcc, 0, v131, vcc
	v_add_u32_e32 v149, 0x2000, v133
	ds_read2_b64 v[142:145], v149 offset1:16
	s_waitcnt vmcnt(0) lgkmcnt(0)
	v_or_b32_e32 v148, v132, v148
	s_mov_b64 s[0:1], 0x112000
	v_mov_b32_e32 v147, 0x7fc00000
	v_cmp_ne_u32_e32 vcc, 0, v148
	v_pk_mul_f32 v[152:153], v[126:127], v[142:143] op_sel:[0,1]
	v_pk_mul_f32 v[156:157], v[128:129], v[142:143] op_sel:[0,1]
	v_lshl_add_u64 v[126:127], v[130:131], 0, s[0:1]
	v_lshl_add_u64 v[158:159], v[134:135], 2, s[94:95]
	v_or_b32_e32 v160, 32, v154
	v_mov_b32_e32 v161, v155
	s_nop 0
	v_lshl_add_u64 v[160:161], s[56:57], 0, v[160:161]
	v_pk_mul_f32 v[124:125], v[124:125], v[142:143] op_sel:[0,1]
	v_pk_mul_f32 v[122:123], v[122:123], v[142:143] op_sel:[0,1]
	v_pk_mul_f32 v[120:121], v[120:121], v[142:143] op_sel:[0,1]
	v_pk_mul_f32 v[118:119], v[118:119], v[142:143] op_sel:[0,1]
	v_pk_mul_f32 v[112:113], v[112:113], v[142:143] op_sel:[0,1]
	v_pk_mul_f32 v[110:111], v[110:111], v[142:143] op_sel:[0,1]
	v_pk_mul_f32 v[114:115], v[114:115], v[144:145] op_sel:[0,1]
	v_pk_mul_f32 v[108:109], v[108:109], v[144:145] op_sel:[0,1]
	v_pk_mul_f32 v[106:107], v[106:107], v[144:145] op_sel:[0,1]
	v_pk_mul_f32 v[104:105], v[104:105], v[144:145] op_sel:[0,1]
	v_pk_mul_f32 v[102:103], v[102:103], v[144:145] op_sel:[0,1]
	v_pk_mul_f32 v[100:101], v[100:101], v[144:145] op_sel:[0,1]
	v_pk_mul_f32 v[98:99], v[98:99], v[144:145] op_sel:[0,1]
	v_lshlrev_b32_e32 v162, 16, v164
	v_and_b32_e32 v163, 0xffff0000, v164
	v_lshlrev_b32_e32 v150, 16, v165
	v_and_b32_e32 v151, 0xffff0000, v165
	v_pk_fma_f32 v[156:157], v[234:235], v[156:157], v[150:151]
	v_pk_fma_f32 v[150:151], v[232:233], v[152:153], v[162:163]
	v_cndmask_b32_e32 v153, v157, v147, vcc
	v_cndmask_b32_e32 v151, v151, v147, vcc
	v_cndmask_b32_e32 v150, v150, v147, vcc
	v_cndmask_b32_e32 v152, v156, v147, vcc
	global_store_dwordx4 v[158:159], v[150:153], off sc1 nt
	v_lshlrev_b32_e32 v156, 16, v166
	v_and_b32_e32 v157, 0xffff0000, v166
	v_lshlrev_b32_e32 v150, 16, v167
	v_and_b32_e32 v151, 0xffff0000, v167
	v_pk_fma_f32 v[122:123], v[236:237], v[122:123], v[156:157]
	v_pk_fma_f32 v[124:125], v[238:239], v[124:125], v[150:151]
	v_or_b32_e32 v152, 0x100, v154
	v_mov_b32_e32 v153, v155
	v_cndmask_b32_e32 v125, v125, v147, vcc
	v_cndmask_b32_e32 v124, v124, v147, vcc
	v_cndmask_b32_e32 v123, v123, v147, vcc
	v_cndmask_b32_e32 v122, v122, v147, vcc
	v_lshl_add_u64 v[152:153], s[56:57], 0, v[152:153]
	global_store_dwordx4 v[158:159], v[122:125], off offset:64 sc1 nt
	s_nop 1
	v_or_b32_e32 v154, 0x120, v154
	v_lshl_add_u64 v[124:125], s[56:57], 0, v[154:155]
	v_lshlrev_b32_e32 v150, 16, v168
	v_and_b32_e32 v151, 0xffff0000, v168
	v_lshlrev_b32_e32 v122, 16, v169
	v_and_b32_e32 v123, 0xffff0000, v169
	v_pk_fma_f32 v[118:119], v[240:241], v[118:119], v[150:151]
	v_pk_fma_f32 v[120:121], v[242:243], v[120:121], v[122:123]
	v_cndmask_b32_e32 v119, v119, v147, vcc
	v_cndmask_b32_e32 v121, v121, v147, vcc
	v_cndmask_b32_e32 v120, v120, v147, vcc
	v_cndmask_b32_e32 v118, v118, v147, vcc
	global_store_dwordx4 v[158:159], v[118:121], off offset:512 sc1 nt
	s_nop 1
	v_lshlrev_b32_e32 v142, 16, v170
	v_add_u32_e32 v120, 16, v146
	v_ashrrev_i32_e32 v121, 31, v120
	v_lshlrev_b64 v[120:121], 10, v[120:121]
	v_and_b32_e32 v143, 0xffff0000, v170
	v_lshlrev_b32_e32 v118, 16, v171
	v_and_b32_e32 v119, 0xffff0000, v171
	v_lshl_add_u64 v[120:121], v[120:121], 0, v[0:1]
	v_pk_fma_f32 v[110:111], v[244:245], v[110:111], v[142:143]
	v_pk_fma_f32 v[112:113], v[246:247], v[112:113], v[118:119]
	v_lshlrev_b64 v[122:123], 1, v[120:121]
	v_cndmask_b32_e32 v113, v113, v147, vcc
	v_cndmask_b32_e32 v112, v112, v147, vcc
	v_cndmask_b32_e32 v111, v111, v147, vcc
	v_cndmask_b32_e32 v110, v110, v147, vcc
	v_lshl_add_u64 v[124:125], s[56:57], 0, v[122:123]
	global_store_dwordx4 v[158:159], v[110:113], off offset:576 sc1 nt
	s_nop 1
	v_or_b32_e32 v118, 32, v122
	v_pk_mul_f32 v[112:113], v[116:117], v[144:145] op_sel:[0,1]
	v_lshl_add_u64 v[116:117], v[120:121], 2, s[94:95]
	v_mov_b32_e32 v119, v123
	v_lshl_add_u64 v[118:119], s[56:57], 0, v[118:119]
	v_lshlrev_b32_e32 v120, 16, v172
	v_and_b32_e32 v121, 0xffff0000, v172
	v_lshlrev_b32_e32 v110, 16, v173
	v_and_b32_e32 v111, 0xffff0000, v173
	v_pk_fma_f32 v[114:115], v[232:233], v[114:115], v[120:121]
	v_pk_fma_f32 v[110:111], v[234:235], v[112:113], v[110:111]
	s_nop 0
	v_cndmask_b32_e32 v113, v111, v147, vcc
	v_cndmask_b32_e32 v112, v110, v147, vcc
	v_cndmask_b32_e32 v111, v115, v147, vcc
	v_cndmask_b32_e32 v110, v114, v147, vcc
	global_store_dwordx4 v[116:117], v[110:113], off sc1 nt
	v_lshlrev_b32_e32 v114, 16, v174
	v_and_b32_e32 v115, 0xffff0000, v174
	v_lshlrev_b32_e32 v110, 16, v175
	v_and_b32_e32 v111, 0xffff0000, v175
	v_pk_fma_f32 v[106:107], v[236:237], v[106:107], v[114:115]
	v_pk_fma_f32 v[108:109], v[238:239], v[108:109], v[110:111]
	v_or_b32_e32 v112, 0x100, v122
	v_mov_b32_e32 v113, v123
	v_cndmask_b32_e32 v109, v109, v147, vcc
	v_cndmask_b32_e32 v108, v108, v147, vcc
	v_cndmask_b32_e32 v107, v107, v147, vcc
	v_cndmask_b32_e32 v106, v106, v147, vcc
	v_lshl_add_u64 v[112:113], s[56:57], 0, v[112:113]
	global_store_dwordx4 v[116:117], v[106:109], off offset:64 sc1 nt
	s_nop 1
	v_or_b32_e32 v122, 0x120, v122
	v_lshl_add_u64 v[108:109], s[56:57], 0, v[122:123]
	v_lshlrev_b32_e32 v110, 16, v176
	v_and_b32_e32 v111, 0xffff0000, v176
	v_lshlrev_b32_e32 v106, 16, v177
	v_and_b32_e32 v107, 0xffff0000, v177
	v_pk_fma_f32 v[102:103], v[240:241], v[102:103], v[110:111]
	v_pk_fma_f32 v[104:105], v[242:243], v[104:105], v[106:107]
	v_cndmask_b32_e32 v103, v103, v147, vcc
	v_cndmask_b32_e32 v105, v105, v147, vcc
	v_cndmask_b32_e32 v104, v104, v147, vcc
	v_cndmask_b32_e32 v102, v102, v147, vcc
	global_store_dwordx4 v[116:117], v[102:105], off offset:512 sc1 nt
	s_nop 1
	v_lshlrev_b32_e32 v110, 16, v178
	v_add_u32_e32 v104, 32, v146
	v_ashrrev_i32_e32 v105, 31, v104
	v_and_b32_e32 v111, 0xffff0000, v178
	v_lshlrev_b32_e32 v102, 16, v179
	v_and_b32_e32 v103, 0xffff0000, v179
	v_lshlrev_b64 v[104:105], 10, v[104:105]
	v_pk_fma_f32 v[98:99], v[244:245], v[98:99], v[110:111]
	v_pk_fma_f32 v[100:101], v[246:247], v[100:101], v[102:103]
	v_lshl_add_u64 v[104:105], v[104:105], 0, v[0:1]
	v_cndmask_b32_e32 v101, v101, v147, vcc
	v_cndmask_b32_e32 v100, v100, v147, vcc
	v_cndmask_b32_e32 v99, v99, v147, vcc
	v_cndmask_b32_e32 v98, v98, v147, vcc
	v_lshlrev_b64 v[106:107], 1, v[104:105]
	global_store_dwordx4 v[116:117], v[98:101], off offset:576 sc1 nt
	v_lshl_add_u64 v[108:109], s[56:57], 0, v[106:107]
	ds_read2_b64 v[98:101], v149 offset0:32 offset1:48
	v_lshl_add_u64 v[104:105], v[104:105], 2, s[94:95]
	v_or_b32_e32 v108, 32, v106
	v_mov_b32_e32 v109, v107
	v_lshl_add_u64 v[108:109], s[56:57], 0, v[108:109]
	s_waitcnt lgkmcnt(0)
	v_pk_mul_f32 v[96:97], v[96:97], v[98:99] op_sel:[0,1]
	v_pk_mul_f32 v[94:95], v[94:95], v[98:99] op_sel:[0,1]
	v_pk_mul_f32 v[92:93], v[92:93], v[98:99] op_sel:[0,1]
	v_pk_mul_f32 v[90:91], v[90:91], v[98:99] op_sel:[0,1]
	v_pk_mul_f32 v[88:89], v[88:89], v[98:99] op_sel:[0,1]
	v_pk_mul_f32 v[86:87], v[86:87], v[98:99] op_sel:[0,1]
	v_pk_mul_f32 v[84:85], v[84:85], v[98:99] op_sel:[0,1]
	v_pk_mul_f32 v[82:83], v[82:83], v[98:99] op_sel:[0,1]
	v_pk_mul_f32 v[80:81], v[80:81], v[100:101] op_sel:[0,1]
	v_pk_mul_f32 v[78:79], v[78:79], v[100:101] op_sel:[0,1]
	v_pk_mul_f32 v[76:77], v[76:77], v[100:101] op_sel:[0,1]
	v_pk_mul_f32 v[74:75], v[74:75], v[100:101] op_sel:[0,1]
	v_pk_mul_f32 v[72:73], v[72:73], v[100:101] op_sel:[0,1]
	v_pk_mul_f32 v[70:71], v[70:71], v[100:101] op_sel:[0,1]
	v_pk_mul_f32 v[68:69], v[68:69], v[100:101] op_sel:[0,1]
	v_pk_mul_f32 v[66:67], v[66:67], v[100:101] op_sel:[0,1]
	v_lshlrev_b32_e32 v110, 16, v180
	v_and_b32_e32 v111, 0xffff0000, v180
	v_lshlrev_b32_e32 v102, 16, v181
	v_and_b32_e32 v103, 0xffff0000, v181
	v_pk_fma_f32 v[94:95], v[232:233], v[94:95], v[110:111]
	v_pk_fma_f32 v[96:97], v[234:235], v[96:97], v[102:103]
	v_cndmask_b32_e32 v95, v95, v147, vcc
	v_cndmask_b32_e32 v97, v97, v147, vcc
	v_cndmask_b32_e32 v96, v96, v147, vcc
	v_cndmask_b32_e32 v94, v94, v147, vcc
	global_store_dwordx4 v[104:105], v[94:97], off sc1 nt
	v_lshlrev_b32_e32 v102, 16, v182
	v_and_b32_e32 v103, 0xffff0000, v182
	v_lshlrev_b32_e32 v94, 16, v183
	v_and_b32_e32 v95, 0xffff0000, v183
	v_pk_fma_f32 v[90:91], v[236:237], v[90:91], v[102:103]
	v_pk_fma_f32 v[92:93], v[238:239], v[92:93], v[94:95]
	v_or_b32_e32 v96, 0x100, v106
	v_mov_b32_e32 v97, v107
	v_cndmask_b32_e32 v93, v93, v147, vcc
	v_cndmask_b32_e32 v92, v92, v147, vcc
	v_cndmask_b32_e32 v91, v91, v147, vcc
	v_cndmask_b32_e32 v90, v90, v147, vcc
	v_lshl_add_u64 v[96:97], s[56:57], 0, v[96:97]
	global_store_dwordx4 v[104:105], v[90:93], off offset:64 sc1 nt
	s_nop 1
	v_or_b32_e32 v106, 0x120, v106
	v_lshl_add_u64 v[92:93], s[56:57], 0, v[106:107]
	v_lshlrev_b32_e32 v94, 16, v184
	v_and_b32_e32 v95, 0xffff0000, v184
	v_lshlrev_b32_e32 v90, 16, v185
	v_and_b32_e32 v91, 0xffff0000, v185
	v_pk_fma_f32 v[86:87], v[240:241], v[86:87], v[94:95]
	v_pk_fma_f32 v[88:89], v[242:243], v[88:89], v[90:91]
	v_cndmask_b32_e32 v87, v87, v147, vcc
	v_cndmask_b32_e32 v89, v89, v147, vcc
	v_cndmask_b32_e32 v88, v88, v147, vcc
	v_cndmask_b32_e32 v86, v86, v147, vcc
	global_store_dwordx4 v[104:105], v[86:89], off offset:512 sc1 nt
	s_nop 1
	v_lshlrev_b32_e32 v94, 16, v186
	v_add_u32_e32 v88, 48, v146
	v_ashrrev_i32_e32 v89, 31, v88
	v_lshlrev_b64 v[88:89], 10, v[88:89]
	v_and_b32_e32 v95, 0xffff0000, v186
	v_lshlrev_b32_e32 v86, 16, v187
	v_and_b32_e32 v87, 0xffff0000, v187
	v_lshl_add_u64 v[88:89], v[88:89], 0, v[0:1]
	v_pk_fma_f32 v[82:83], v[244:245], v[82:83], v[94:95]
	v_pk_fma_f32 v[84:85], v[246:247], v[84:85], v[86:87]
	v_lshlrev_b64 v[90:91], 1, v[88:89]
	v_cndmask_b32_e32 v85, v85, v147, vcc
	v_cndmask_b32_e32 v84, v84, v147, vcc
	v_cndmask_b32_e32 v83, v83, v147, vcc
	v_cndmask_b32_e32 v82, v82, v147, vcc
	v_lshl_add_u64 v[92:93], s[56:57], 0, v[90:91]
	global_store_dwordx4 v[104:105], v[82:85], off offset:576 sc1 nt
	s_nop 1
	v_or_b32_e32 v86, 32, v90
	v_lshl_add_u64 v[84:85], v[88:89], 2, s[94:95]
	v_mov_b32_e32 v87, v91
	v_lshl_add_u64 v[86:87], s[56:57], 0, v[86:87]
	v_lshlrev_b32_e32 v88, 16, v188
	v_and_b32_e32 v89, 0xffff0000, v188
	v_lshlrev_b32_e32 v82, 16, v189
	v_and_b32_e32 v83, 0xffff0000, v189
	v_pk_fma_f32 v[78:79], v[232:233], v[78:79], v[88:89]
	v_pk_fma_f32 v[80:81], v[234:235], v[80:81], v[82:83]
	v_cndmask_b32_e32 v79, v79, v147, vcc
	v_cndmask_b32_e32 v81, v81, v147, vcc
	v_cndmask_b32_e32 v80, v80, v147, vcc
	v_cndmask_b32_e32 v78, v78, v147, vcc
	global_store_dwordx4 v[84:85], v[78:81], off sc1 nt
	v_lshlrev_b32_e32 v82, 16, v190
	v_and_b32_e32 v83, 0xffff0000, v190
	v_lshlrev_b32_e32 v78, 16, v191
	v_and_b32_e32 v79, 0xffff0000, v191
	v_pk_fma_f32 v[74:75], v[236:237], v[74:75], v[82:83]
	v_pk_fma_f32 v[76:77], v[238:239], v[76:77], v[78:79]
	v_or_b32_e32 v80, 0x100, v90
	v_mov_b32_e32 v81, v91
	v_cndmask_b32_e32 v77, v77, v147, vcc
	v_cndmask_b32_e32 v76, v76, v147, vcc
	v_cndmask_b32_e32 v75, v75, v147, vcc
	v_cndmask_b32_e32 v74, v74, v147, vcc
	v_lshl_add_u64 v[80:81], s[56:57], 0, v[80:81]
	global_store_dwordx4 v[84:85], v[74:77], off offset:64 sc1 nt
	s_nop 1
	v_or_b32_e32 v90, 0x120, v90
	v_lshl_add_u64 v[76:77], s[56:57], 0, v[90:91]
	v_lshlrev_b32_e32 v78, 16, v192
	v_and_b32_e32 v79, 0xffff0000, v192
	v_lshlrev_b32_e32 v74, 16, v193
	v_and_b32_e32 v75, 0xffff0000, v193
	v_pk_fma_f32 v[70:71], v[240:241], v[70:71], v[78:79]
	v_pk_fma_f32 v[72:73], v[242:243], v[72:73], v[74:75]
	v_cndmask_b32_e32 v71, v71, v147, vcc
	v_cndmask_b32_e32 v73, v73, v147, vcc
	v_cndmask_b32_e32 v72, v72, v147, vcc
	v_cndmask_b32_e32 v70, v70, v147, vcc
	global_store_dwordx4 v[84:85], v[70:73], off offset:512 sc1 nt
	s_nop 1
	v_lshlrev_b32_e32 v78, 16, v194
	v_add_u32_e32 v72, 0x80, v146
	v_ashrrev_i32_e32 v73, 31, v72
	v_and_b32_e32 v79, 0xffff0000, v194
	v_lshlrev_b32_e32 v70, 16, v195
	v_and_b32_e32 v71, 0xffff0000, v195
	v_lshlrev_b64 v[72:73], 10, v[72:73]
	v_pk_fma_f32 v[66:67], v[244:245], v[66:67], v[78:79]
	v_pk_fma_f32 v[68:69], v[246:247], v[68:69], v[70:71]
	v_lshl_add_u64 v[72:73], v[72:73], 0, v[0:1]
	v_cndmask_b32_e32 v69, v69, v147, vcc
	v_cndmask_b32_e32 v68, v68, v147, vcc
	v_cndmask_b32_e32 v67, v67, v147, vcc
	v_cndmask_b32_e32 v66, v66, v147, vcc
	v_lshlrev_b64 v[74:75], 1, v[72:73]
	global_store_dwordx4 v[84:85], v[66:69], off offset:576 sc1 nt
	v_lshl_add_u64 v[76:77], s[56:57], 0, v[74:75]
	ds_read2_b64 v[66:69], v149 offset0:128 offset1:144
	v_lshl_add_u64 v[72:73], v[72:73], 2, s[94:95]
	v_or_b32_e32 v76, 32, v74
	v_mov_b32_e32 v77, v75
	v_lshl_add_u64 v[76:77], s[56:57], 0, v[76:77]
	s_waitcnt lgkmcnt(0)
	v_pk_mul_f32 v[64:65], v[64:65], v[66:67] op_sel:[0,1]
	v_pk_mul_f32 v[62:63], v[62:63], v[66:67] op_sel:[0,1]
	v_pk_mul_f32 v[60:61], v[60:61], v[66:67] op_sel:[0,1]
	v_pk_mul_f32 v[58:59], v[58:59], v[66:67] op_sel:[0,1]
	v_pk_mul_f32 v[56:57], v[56:57], v[66:67] op_sel:[0,1]
	v_pk_mul_f32 v[54:55], v[54:55], v[66:67] op_sel:[0,1]
	v_pk_mul_f32 v[52:53], v[52:53], v[66:67] op_sel:[0,1]
	v_pk_mul_f32 v[50:51], v[50:51], v[66:67] op_sel:[0,1]
	v_pk_mul_f32 v[48:49], v[48:49], v[68:69] op_sel:[0,1]
	v_pk_mul_f32 v[46:47], v[46:47], v[68:69] op_sel:[0,1]
	v_pk_mul_f32 v[44:45], v[44:45], v[68:69] op_sel:[0,1]
	v_pk_mul_f32 v[42:43], v[42:43], v[68:69] op_sel:[0,1]
	v_pk_mul_f32 v[40:41], v[40:41], v[68:69] op_sel:[0,1]
	v_pk_mul_f32 v[38:39], v[38:39], v[68:69] op_sel:[0,1]
	v_pk_mul_f32 v[36:37], v[36:37], v[68:69] op_sel:[0,1]
	v_pk_mul_f32 v[34:35], v[34:35], v[68:69] op_sel:[0,1]
	v_lshlrev_b32_e32 v78, 16, v196
	v_and_b32_e32 v79, 0xffff0000, v196
	v_lshlrev_b32_e32 v70, 16, v197
	v_and_b32_e32 v71, 0xffff0000, v197
	v_pk_fma_f32 v[62:63], v[232:233], v[62:63], v[78:79]
	v_pk_fma_f32 v[64:65], v[234:235], v[64:65], v[70:71]
	v_cndmask_b32_e32 v63, v63, v147, vcc
	v_cndmask_b32_e32 v65, v65, v147, vcc
	v_cndmask_b32_e32 v64, v64, v147, vcc
	v_cndmask_b32_e32 v62, v62, v147, vcc
	global_store_dwordx4 v[72:73], v[62:65], off sc1 nt
	v_lshlrev_b32_e32 v70, 16, v198
	v_and_b32_e32 v71, 0xffff0000, v198
	v_lshlrev_b32_e32 v62, 16, v199
	v_and_b32_e32 v63, 0xffff0000, v199
	v_pk_fma_f32 v[58:59], v[236:237], v[58:59], v[70:71]
	v_pk_fma_f32 v[60:61], v[238:239], v[60:61], v[62:63]
	v_or_b32_e32 v64, 0x100, v74
	v_mov_b32_e32 v65, v75
	v_cndmask_b32_e32 v61, v61, v147, vcc
	v_cndmask_b32_e32 v60, v60, v147, vcc
	v_cndmask_b32_e32 v59, v59, v147, vcc
	v_cndmask_b32_e32 v58, v58, v147, vcc
	v_lshl_add_u64 v[64:65], s[56:57], 0, v[64:65]
	global_store_dwordx4 v[72:73], v[58:61], off offset:64 sc1 nt
	s_nop 1
	v_or_b32_e32 v74, 0x120, v74
	v_lshl_add_u64 v[60:61], s[56:57], 0, v[74:75]
	v_lshlrev_b32_e32 v62, 16, v200
	v_and_b32_e32 v63, 0xffff0000, v200
	v_lshlrev_b32_e32 v58, 16, v201
	v_and_b32_e32 v59, 0xffff0000, v201
	v_pk_fma_f32 v[54:55], v[240:241], v[54:55], v[62:63]
	v_pk_fma_f32 v[56:57], v[242:243], v[56:57], v[58:59]
	v_cndmask_b32_e32 v55, v55, v147, vcc
	v_cndmask_b32_e32 v57, v57, v147, vcc
	v_cndmask_b32_e32 v56, v56, v147, vcc
	v_cndmask_b32_e32 v54, v54, v147, vcc
	global_store_dwordx4 v[72:73], v[54:57], off offset:512 sc1 nt
	s_nop 1
	v_lshlrev_b32_e32 v62, 16, v204
	v_add_u32_e32 v56, 0x90, v146
	v_ashrrev_i32_e32 v57, 31, v56
	v_lshlrev_b64 v[56:57], 10, v[56:57]
	v_and_b32_e32 v63, 0xffff0000, v204
	v_lshlrev_b32_e32 v54, 16, v205
	v_and_b32_e32 v55, 0xffff0000, v205
	v_lshl_add_u64 v[56:57], v[56:57], 0, v[0:1]
	v_pk_fma_f32 v[50:51], v[244:245], v[50:51], v[62:63]
	v_pk_fma_f32 v[52:53], v[246:247], v[52:53], v[54:55]
	v_lshlrev_b64 v[58:59], 1, v[56:57]
	v_cndmask_b32_e32 v53, v53, v147, vcc
	v_cndmask_b32_e32 v52, v52, v147, vcc
	v_cndmask_b32_e32 v51, v51, v147, vcc
	v_cndmask_b32_e32 v50, v50, v147, vcc
	v_lshl_add_u64 v[60:61], s[56:57], 0, v[58:59]
	global_store_dwordx4 v[72:73], v[50:53], off offset:576 sc1 nt
	s_nop 1
	v_or_b32_e32 v54, 32, v58
	v_lshl_add_u64 v[52:53], v[56:57], 2, s[94:95]
	v_mov_b32_e32 v55, v59
	v_lshl_add_u64 v[54:55], s[56:57], 0, v[54:55]
	v_lshlrev_b32_e32 v56, 16, v206
	v_and_b32_e32 v57, 0xffff0000, v206
	v_lshlrev_b32_e32 v50, 16, v207
	v_and_b32_e32 v51, 0xffff0000, v207
	v_pk_fma_f32 v[46:47], v[232:233], v[46:47], v[56:57]
	v_pk_fma_f32 v[48:49], v[234:235], v[48:49], v[50:51]
	v_cndmask_b32_e32 v47, v47, v147, vcc
	v_cndmask_b32_e32 v49, v49, v147, vcc
	v_cndmask_b32_e32 v48, v48, v147, vcc
	v_cndmask_b32_e32 v46, v46, v147, vcc
	global_store_dwordx4 v[52:53], v[46:49], off sc1 nt
	v_lshlrev_b32_e32 v50, 16, v208
	v_and_b32_e32 v51, 0xffff0000, v208
	v_lshlrev_b32_e32 v46, 16, v209
	v_and_b32_e32 v47, 0xffff0000, v209
	v_pk_fma_f32 v[42:43], v[236:237], v[42:43], v[50:51]
	v_pk_fma_f32 v[44:45], v[238:239], v[44:45], v[46:47]
	v_or_b32_e32 v48, 0x100, v58
	v_mov_b32_e32 v49, v59
	v_cndmask_b32_e32 v45, v45, v147, vcc
	v_cndmask_b32_e32 v44, v44, v147, vcc
	v_cndmask_b32_e32 v43, v43, v147, vcc
	v_cndmask_b32_e32 v42, v42, v147, vcc
	v_lshl_add_u64 v[48:49], s[56:57], 0, v[48:49]
	global_store_dwordx4 v[52:53], v[42:45], off offset:64 sc1 nt
	s_nop 1
	v_or_b32_e32 v58, 0x120, v58
	v_lshl_add_u64 v[44:45], s[56:57], 0, v[58:59]
	v_lshlrev_b32_e32 v46, 16, v210
	v_and_b32_e32 v47, 0xffff0000, v210
	v_lshlrev_b32_e32 v42, 16, v211
	v_and_b32_e32 v43, 0xffff0000, v211
	v_pk_fma_f32 v[38:39], v[240:241], v[38:39], v[46:47]
	v_pk_fma_f32 v[40:41], v[242:243], v[40:41], v[42:43]
	v_cndmask_b32_e32 v39, v39, v147, vcc
	v_cndmask_b32_e32 v41, v41, v147, vcc
	v_cndmask_b32_e32 v40, v40, v147, vcc
	v_cndmask_b32_e32 v38, v38, v147, vcc
	global_store_dwordx4 v[52:53], v[38:41], off offset:512 sc1 nt
	s_nop 1
	v_lshlrev_b32_e32 v46, 16, v212
	v_add_u32_e32 v40, 0xa0, v146
	v_ashrrev_i32_e32 v41, 31, v40
	v_and_b32_e32 v47, 0xffff0000, v212
	v_lshlrev_b32_e32 v38, 16, v213
	v_and_b32_e32 v39, 0xffff0000, v213
	v_lshlrev_b64 v[40:41], 10, v[40:41]
	v_pk_fma_f32 v[34:35], v[244:245], v[34:35], v[46:47]
	v_pk_fma_f32 v[36:37], v[246:247], v[36:37], v[38:39]
	v_lshl_add_u64 v[40:41], v[40:41], 0, v[0:1]
	v_cndmask_b32_e32 v37, v37, v147, vcc
	v_cndmask_b32_e32 v36, v36, v147, vcc
	v_cndmask_b32_e32 v35, v35, v147, vcc
	v_cndmask_b32_e32 v34, v34, v147, vcc
	v_lshlrev_b64 v[42:43], 1, v[40:41]
	global_store_dwordx4 v[52:53], v[34:37], off offset:576 sc1 nt
	v_lshl_add_u64 v[44:45], s[56:57], 0, v[42:43]
	ds_read2_b64 v[34:37], v149 offset0:160 offset1:176
	v_lshl_add_u64 v[40:41], v[40:41], 2, s[94:95]
	v_or_b32_e32 v44, 32, v42
	v_mov_b32_e32 v45, v43
	v_lshl_add_u64 v[44:45], s[56:57], 0, v[44:45]
	s_waitcnt lgkmcnt(0)
	v_pk_mul_f32 v[32:33], v[32:33], v[34:35] op_sel:[0,1]
	v_pk_mul_f32 v[30:31], v[30:31], v[34:35] op_sel:[0,1]
	v_pk_mul_f32 v[28:29], v[28:29], v[34:35] op_sel:[0,1]
	v_pk_mul_f32 v[26:27], v[26:27], v[34:35] op_sel:[0,1]
	v_pk_mul_f32 v[24:25], v[24:25], v[34:35] op_sel:[0,1]
	v_pk_mul_f32 v[22:23], v[22:23], v[34:35] op_sel:[0,1]
	v_pk_mul_f32 v[20:21], v[20:21], v[34:35] op_sel:[0,1]
	v_pk_mul_f32 v[18:19], v[18:19], v[34:35] op_sel:[0,1]
	v_pk_mul_f32 v[16:17], v[16:17], v[36:37] op_sel:[0,1]
	v_pk_mul_f32 v[14:15], v[14:15], v[36:37] op_sel:[0,1]
	v_pk_mul_f32 v[12:13], v[12:13], v[36:37] op_sel:[0,1]
	v_pk_mul_f32 v[10:11], v[10:11], v[36:37] op_sel:[0,1]
	v_pk_mul_f32 v[8:9], v[8:9], v[36:37] op_sel:[0,1]
	v_pk_mul_f32 v[6:7], v[6:7], v[36:37] op_sel:[0,1]
	v_pk_mul_f32 v[4:5], v[4:5], v[36:37] op_sel:[0,1]
	v_pk_mul_f32 v[2:3], v[2:3], v[36:37] op_sel:[0,1]
	v_lshlrev_b32_e32 v46, 16, v214
	v_and_b32_e32 v47, 0xffff0000, v214
	v_lshlrev_b32_e32 v38, 16, v215
	v_and_b32_e32 v39, 0xffff0000, v215
	v_pk_fma_f32 v[30:31], v[232:233], v[30:31], v[46:47]
	v_pk_fma_f32 v[32:33], v[234:235], v[32:33], v[38:39]
	v_cndmask_b32_e32 v31, v31, v147, vcc
	v_cndmask_b32_e32 v33, v33, v147, vcc
	v_cndmask_b32_e32 v32, v32, v147, vcc
	v_cndmask_b32_e32 v30, v30, v147, vcc
	global_store_dwordx4 v[40:41], v[30:33], off sc1 nt
	v_lshlrev_b32_e32 v38, 16, v216
	v_and_b32_e32 v39, 0xffff0000, v216
	v_lshlrev_b32_e32 v30, 16, v217
	v_and_b32_e32 v31, 0xffff0000, v217
	v_pk_fma_f32 v[26:27], v[236:237], v[26:27], v[38:39]
	v_pk_fma_f32 v[28:29], v[238:239], v[28:29], v[30:31]
	v_or_b32_e32 v32, 0x100, v42
	v_mov_b32_e32 v33, v43
	v_cndmask_b32_e32 v29, v29, v147, vcc
	v_cndmask_b32_e32 v28, v28, v147, vcc
	v_cndmask_b32_e32 v27, v27, v147, vcc
	v_cndmask_b32_e32 v26, v26, v147, vcc
	v_lshl_add_u64 v[32:33], s[56:57], 0, v[32:33]
	global_store_dwordx4 v[40:41], v[26:29], off offset:64 sc1 nt
	s_nop 1
	v_or_b32_e32 v42, 0x120, v42
	v_lshl_add_u64 v[28:29], s[56:57], 0, v[42:43]
	v_lshlrev_b32_e32 v30, 16, v218
	v_and_b32_e32 v31, 0xffff0000, v218
	v_lshlrev_b32_e32 v26, 16, v219
	v_and_b32_e32 v27, 0xffff0000, v219
	v_pk_fma_f32 v[22:23], v[240:241], v[22:23], v[30:31]
	v_pk_fma_f32 v[24:25], v[242:243], v[24:25], v[26:27]
	v_cndmask_b32_e32 v23, v23, v147, vcc
	v_cndmask_b32_e32 v25, v25, v147, vcc
	v_cndmask_b32_e32 v24, v24, v147, vcc
	v_cndmask_b32_e32 v22, v22, v147, vcc
	global_store_dwordx4 v[40:41], v[22:25], off offset:512 sc1 nt
	s_nop 1
	v_lshlrev_b32_e32 v28, 16, v220
	v_add_u32_e32 v24, 0xb0, v146
	v_ashrrev_i32_e32 v25, 31, v24
	v_lshlrev_b64 v[24:25], 10, v[24:25]
	v_and_b32_e32 v29, 0xffff0000, v220
	v_lshlrev_b32_e32 v22, 16, v221
	v_and_b32_e32 v23, 0xffff0000, v221
	v_lshl_add_u64 v[0:1], v[24:25], 0, v[0:1]
	v_pk_fma_f32 v[18:19], v[244:245], v[18:19], v[28:29]
	v_pk_fma_f32 v[20:21], v[246:247], v[20:21], v[22:23]
	v_lshlrev_b64 v[24:25], 1, v[0:1]
	v_cndmask_b32_e32 v21, v21, v147, vcc
	v_cndmask_b32_e32 v20, v20, v147, vcc
	v_cndmask_b32_e32 v19, v19, v147, vcc
	v_cndmask_b32_e32 v18, v18, v147, vcc
	v_lshl_add_u64 v[26:27], s[56:57], 0, v[24:25]
	global_store_dwordx4 v[40:41], v[18:21], off offset:576 sc1 nt
	v_lshlrev_b32_e32 v22, 16, v222
	v_and_b32_e32 v23, 0xffff0000, v222
	v_lshlrev_b32_e32 v18, 16, v223
	v_and_b32_e32 v19, 0xffff0000, v223
	v_pk_fma_f32 v[14:15], v[232:233], v[14:15], v[22:23]
	v_pk_fma_f32 v[16:17], v[234:235], v[16:17], v[18:19]
	v_lshl_add_u64 v[20:21], v[0:1], 2, s[94:95]
	v_or_b32_e32 v0, 32, v24
	v_mov_b32_e32 v1, v25
	v_cndmask_b32_e32 v17, v17, v147, vcc
	v_cndmask_b32_e32 v16, v16, v147, vcc
	v_cndmask_b32_e32 v15, v15, v147, vcc
	v_cndmask_b32_e32 v14, v14, v147, vcc
	v_lshl_add_u64 v[0:1], s[56:57], 0, v[0:1]
	global_store_dwordx4 v[20:21], v[14:17], off sc1 nt
	s_nop 1
	s_nop 0
	v_or_b32_e32 v14, 0x100, v24
	v_mov_b32_e32 v15, v25
	v_lshl_add_u64 v[14:15], s[56:57], 0, v[14:15]
	v_or_b32_e32 v24, 0x120, v24
	v_lshlrev_b32_e32 v16, 16, v224
	v_and_b32_e32 v17, 0xffff0000, v224
	v_lshlrev_b32_e32 v0, 16, v225
	v_and_b32_e32 v1, 0xffff0000, v225
	v_pk_fma_f32 v[10:11], v[236:237], v[10:11], v[16:17]
	v_pk_fma_f32 v[0:1], v[238:239], v[12:13], v[0:1]
	v_cndmask_b32_e32 v11, v11, v147, vcc
	v_cndmask_b32_e32 v13, v1, v147, vcc
	v_cndmask_b32_e32 v12, v0, v147, vcc
	v_cndmask_b32_e32 v10, v10, v147, vcc
	global_store_dwordx4 v[20:21], v[10:13], off offset:64 sc1 nt
	s_nop 1
	s_nop 0
	v_lshl_add_u64 v[10:11], s[56:57], 0, v[24:25]
	v_lshlrev_b32_e32 v12, 16, v226
	v_and_b32_e32 v13, 0xffff0000, v226
	v_lshlrev_b32_e32 v0, 16, v227
	v_and_b32_e32 v1, 0xffff0000, v227
	v_pk_fma_f32 v[6:7], v[240:241], v[6:7], v[12:13]
	v_pk_fma_f32 v[0:1], v[242:243], v[8:9], v[0:1]
	v_cndmask_b32_e32 v7, v7, v147, vcc
	v_cndmask_b32_e32 v9, v1, v147, vcc
	v_cndmask_b32_e32 v8, v0, v147, vcc
	v_cndmask_b32_e32 v6, v6, v147, vcc
	global_store_dwordx4 v[20:21], v[6:9], off offset:512 sc1 nt
	s_nop 1
	v_lshlrev_b32_e32 v6, 16, v228
	v_and_b32_e32 v7, 0xffff0000, v228
	v_lshlrev_b32_e32 v0, 16, v229
	v_and_b32_e32 v1, 0xffff0000, v229
	v_pk_fma_f32 v[6:7], v[244:245], v[2:3], v[6:7]
	v_pk_fma_f32 v[0:1], v[246:247], v[4:5], v[0:1]
	s_nop 0
	v_cndmask_b32_e32 v3, v1, v147, vcc
	v_cndmask_b32_e32 v2, v0, v147, vcc
	v_cndmask_b32_e32 v1, v7, v147, vcc
	v_cndmask_b32_e32 v0, v6, v147, vcc
	global_store_dwordx4 v[20:21], v[0:3], off offset:576 sc1 nt
